# conv_p batched loads made nontemporal (streamed input, read once) to keep the concurrent GEMM round's L2 working set
# baseline (speedup 1.0000x reference)
; __device__ __forceinline__ int tid_() { int t = (int)threadIdx.x; asm volatile("" : "+v"(t)); return t & 511; }
; __device__ __forceinline__ int bid_() { int b = (int)blockIdx.x; asm volatile("" : "+s"(b)); return b; }
; __device__ __forceinline__ int gdim_() { int g = (int)gridDim.x; asm volatile("" : "+s"(g)); return g; }
; DI unsigned pk2(float lo, float hi) { const f32x2v v = {lo, hi}; const bf16x2v b = __builtin_convertvector(v, bf16x2v); return __builtin_bit_cast(unsigned, b); }
; DI void conv_p(const Params& P, int l) {
;     const int gt = bid_() * 512 + tid_(), NT = gdim_() * 512; bf16_t* PB = (bf16_t*)(P.ws + O_PBF);
; #pragma unroll 4
;     for (int i = gt; i < T * 64; i += NT) { const int row = i >> 6, c4 = (i & 63) * 4;
;         const float* src = row < TP ? P.in[I_PP] + ((size_t)l * TP + row) * 256 + c4 : P.in[I_PS] + ((size_t)l * 512 + (row - TP)) * 256 + c4;
;         const f32x4 v = *(const f32x4*)src; u32x2 w; w.x = pk2(v[0], v[1]); w.y = pk2(v[2], v[3]); *(u32x2*)(PB + (size_t)row * 256 + c4) = w; }
.LBB0_905:
	v_and_b32_e32 v0, 0xfc, v1
	v_lshlrev_b32_e32 v2, 2, v0
	v_mov_b32_e32 v3, v25
	v_lshlrev_b32_e32 v24, 1, v0
	v_ashrrev_i32_e32 v30, 6, v8
	v_ashrrev_i32_e32 v31, 31, v30
	v_cmp_lt_i32_e32 vcc, s94, v30
	v_lshl_add_u64 v[38:39], v[30:31], 0, s[36:37]
	v_lshlrev_b64 v[38:39], 10, v[38:39]
	v_lshl_add_u64 v[38:39], s[22:23], 0, v[38:39]
	v_add_u32_e32 v54, s3, v30
	v_add_u32_e32 v54, 0xffffc000, v54
	v_mov_b32_e32 v55, 0
	v_lshlrev_b64 v[46:47], 10, v[54:55]
	v_lshl_add_u64 v[46:47], s[20:21], 0, v[46:47]
	v_cndmask_b32_e32 v38, v38, v46, vcc
	v_cndmask_b32_e32 v39, v39, v47, vcc
	v_lshl_add_u64 v[38:39], v[38:39], 0, v[2:3]
	global_load_dwordx4 v[62:65], v[38:39], off nt
	v_lshlrev_b64 v[78:79], 9, v[30:31]
	v_lshl_add_u64 v[78:79], s[8:9], 0, v[78:79]
	v_lshl_add_u64 v[78:79], v[78:79], 0, v[24:25]
	v_add_u32_e32 v8, s2, v8
	v_ashrrev_i32_e32 v32, 6, v8
	v_ashrrev_i32_e32 v33, 31, v32
	v_cmp_lt_i32_e32 vcc, s94, v32
	v_lshl_add_u64 v[40:41], v[32:33], 0, s[36:37]
	v_lshlrev_b64 v[40:41], 10, v[40:41]
	v_lshl_add_u64 v[40:41], s[22:23], 0, v[40:41]
	v_add_u32_e32 v56, s3, v32
	v_add_u32_e32 v56, 0xffffc000, v56
	v_mov_b32_e32 v57, 0
	v_lshlrev_b64 v[48:49], 10, v[56:57]
	v_lshl_add_u64 v[48:49], s[20:21], 0, v[48:49]
	v_cndmask_b32_e32 v40, v40, v48, vcc
	v_cndmask_b32_e32 v41, v41, v49, vcc
	v_lshl_add_u64 v[40:41], v[40:41], 0, v[2:3]
	global_load_dwordx4 v[66:69], v[40:41], off nt
	v_lshlrev_b64 v[80:81], 9, v[32:33]
	v_lshl_add_u64 v[80:81], s[8:9], 0, v[80:81]
	v_lshl_add_u64 v[80:81], v[80:81], 0, v[24:25]
	v_add_u32_e32 v8, s2, v8
	v_ashrrev_i32_e32 v34, 6, v8
	v_ashrrev_i32_e32 v35, 31, v34
	v_cmp_lt_i32_e32 vcc, s94, v34
	v_lshl_add_u64 v[42:43], v[34:35], 0, s[36:37]
	v_lshlrev_b64 v[42:43], 10, v[42:43]
	v_lshl_add_u64 v[42:43], s[22:23], 0, v[42:43]
	v_add_u32_e32 v58, s3, v34
	v_add_u32_e32 v58, 0xffffc000, v58
	v_mov_b32_e32 v59, 0
	v_lshlrev_b64 v[50:51], 10, v[58:59]
	v_lshl_add_u64 v[50:51], s[20:21], 0, v[50:51]
	v_cndmask_b32_e32 v42, v42, v50, vcc
	v_cndmask_b32_e32 v43, v43, v51, vcc
	v_lshl_add_u64 v[42:43], v[42:43], 0, v[2:3]
	global_load_dwordx4 v[70:73], v[42:43], off nt
	v_lshlrev_b64 v[82:83], 9, v[34:35]
	v_lshl_add_u64 v[82:83], s[8:9], 0, v[82:83]
	v_lshl_add_u64 v[82:83], v[82:83], 0, v[24:25]
	v_add_u32_e32 v8, s2, v8
	v_ashrrev_i32_e32 v36, 6, v8
	v_ashrrev_i32_e32 v37, 31, v36
	v_cmp_lt_i32_e32 vcc, s94, v36
	v_lshl_add_u64 v[44:45], v[36:37], 0, s[36:37]
	v_lshlrev_b64 v[44:45], 10, v[44:45]
	v_lshl_add_u64 v[44:45], s[22:23], 0, v[44:45]
	v_add_u32_e32 v60, s3, v36
	v_add_u32_e32 v60, 0xffffc000, v60
	v_mov_b32_e32 v61, 0
	v_lshlrev_b64 v[52:53], 10, v[60:61]
	v_lshl_add_u64 v[52:53], s[20:21], 0, v[52:53]
	v_cndmask_b32_e32 v44, v44, v52, vcc
	v_cndmask_b32_e32 v45, v45, v53, vcc
	v_lshl_add_u64 v[44:45], v[44:45], 0, v[2:3]
	global_load_dwordx4 v[74:77], v[44:45], off nt
	v_lshlrev_b64 v[84:85], 9, v[36:37]
	v_lshl_add_u64 v[84:85], s[8:9], 0, v[84:85]
	v_lshl_add_u64 v[84:85], v[84:85], 0, v[24:25]
	v_add_u32_e32 v8, s2, v8
	s_mov_b32 s12, 0x107fff
	v_cmp_lt_i32_e32 vcc, s12, v8
	s_or_b64 s[10:11], vcc, s[10:11]
	v_add_u32_e32 v1, s14, v1
	s_waitcnt vmcnt(0)
	v_cvt_pk_bf16_f32 v62, v62, v63
	v_cvt_pk_bf16_f32 v63, v64, v65
	global_store_dwordx2 v[78:79], v[62:63], off
	v_cvt_pk_bf16_f32 v66, v66, v67
	v_cvt_pk_bf16_f32 v67, v68, v69
	global_store_dwordx2 v[80:81], v[66:67], off
	v_cvt_pk_bf16_f32 v70, v70, v71
	v_cvt_pk_bf16_f32 v71, v72, v73
	global_store_dwordx2 v[82:83], v[70:71], off
	v_cvt_pk_bf16_f32 v74, v74, v75
	v_cvt_pk_bf16_f32 v75, v76, v77
	global_store_dwordx2 v[84:85], v[74:75], off
	s_andn2_b64 exec, exec, s[10:11]
	s_cbranch_execnz .LBB0_905
